# barrier leader issues its L1 invalidate under the cross-XCD arrival atomic round trip
# speedup vs baseline: 1.0029x; 1.0029x over previous
; __device__ __forceinline__ unsigned xb_ld(unsigned* p)              { return __hip_atomic_load(p, __ATOMIC_RELAXED, __HIP_MEMORY_SCOPE_AGENT); }
; __device__ __forceinline__ unsigned xb_add(unsigned* p, unsigned v) { return __hip_atomic_fetch_add(p, v, __ATOMIC_RELAXED, __HIP_MEMORY_SCOPE_AGENT); }
; #define XB_SPIN(cond, bar) do { unsigned _sp = 0; while (cond) { __builtin_amdgcn_s_sleep(1); \
;     if ((++_sp & 255u) == 0u) { if (xb_ld(&(bar)[XB_TMO])) break; if (_sp > XB_SPIN_CAP) { atomicAdd(&(bar)[XB_TMO], 1u); break; } } } } while (0)
; __device__ __forceinline__ void xcd_barrier(const XcdBarrier& b) {
;     ...
;         if (old + 1u == (gen + 1u) * nloc) {
;             __builtin_amdgcn_fence(__ATOMIC_RELEASE, "agent");
;             asm volatile("s_waitcnt vmcnt(0)" ::: "memory");
;             const unsigned og = xb_add(&bar[XB_TOP], 1u);
;             const unsigned tg = og / nx;
;             if (og + 1u == (tg + 1u) * nx) xb_add(&bar[XB_TOPGEN], 1u);
;             else XB_SPIN(xb_ld(&bar[XB_TOPGEN]) == tg, bar);
.LBB0_118:
	s_or_b64 exec, exec, s[12:13]
	buffer_inv sc1
	v_cvt_f32_u32_e32 v4, v1
	s_waitcnt vmcnt(1)
	v_readfirstlane_b32 s2, v3
	s_load_dwordx8 s[12:19], s[0:1], 0x100
	s_waitcnt lgkmcnt(0)
	s_mov_b64 s[14:15], -1
	v_rcp_iflag_f32_e32 v4, v4
	v_add_u32_e32 v2, s2, v2
	v_add_u32_e32 v5, 1, v2
	s_add_u32 s12, s18, 0x7500
	v_mul_f32_e32 v3, 0x4f7ffffe, v4
	v_cvt_u32_f32_e32 v3, v3
	v_sub_u32_e32 v4, 0, v1
	s_addc_u32 s13, s19, 0
	v_mul_lo_u32 v4, v4, v3
	v_mul_hi_u32 v4, v3, v4
	v_add_u32_e32 v3, v3, v4
	v_mul_hi_u32 v3, v2, v3
	v_mul_lo_u32 v4, v3, v1
	v_sub_u32_e32 v2, v2, v4
	v_add_u32_e32 v6, 1, v3
	v_cmp_ge_u32_e32 vcc, v2, v1
	v_sub_u32_e32 v4, v2, v1
	s_nop 0
	v_cndmask_b32_e32 v3, v3, v6, vcc
	v_cndmask_b32_e32 v2, v2, v4, vcc
	v_add_u32_e32 v4, 1, v3
	v_cmp_ge_u32_e32 vcc, v2, v1
	s_nop 1
	v_cndmask_b32_e32 v4, v3, v4, vcc
	v_mul_lo_u32 v2, v1, v4
	v_add_u32_e32 v1, v2, v1
	v_cmp_ne_u32_e32 vcc, v5, v1
	v_mov_b64_e32 v[2:3], s[12:13]
	s_and_saveexec_b64 s[10:11], vcc
	s_cbranch_execz .LBB0_130
	v_mov_b32_e32 v1, 0
	global_load_dword v2, v1, s[12:13] sc1
	s_mov_b64 s[18:19], 0
	s_waitcnt vmcnt(0)
	v_cmp_eq_u32_e32 vcc, v2, v4
	s_and_saveexec_b64 s[16:17], vcc
	s_cbranch_execz .LBB0_129
	s_load_dwordx8 s[20:27], s[0:1], 0x100
	s_mov_b32 s2, 1
	s_waitcnt lgkmcnt(0)
	s_add_u32 s14, s26, 0x4200
	s_addc_u32 s15, s27, 0
	s_branch .LBB0_122

; __device__ __forceinline__ unsigned xb_ld(unsigned* p)              { return __hip_atomic_load(p, __ATOMIC_RELAXED, __HIP_MEMORY_SCOPE_AGENT); }
; __device__ __forceinline__ unsigned xb_add(unsigned* p, unsigned v) { return __hip_atomic_fetch_add(p, v, __ATOMIC_RELAXED, __HIP_MEMORY_SCOPE_AGENT); }
; #define XB_SPIN(cond, bar) do { unsigned _sp = 0; while (cond) { __builtin_amdgcn_s_sleep(1); \
;     if ((++_sp & 255u) == 0u) { if (xb_ld(&(bar)[XB_TMO])) break; if (_sp > XB_SPIN_CAP) { atomicAdd(&(bar)[XB_TMO], 1u); break; } } } } while (0)
; __device__ __forceinline__ void xcd_barrier(const XcdBarrier& b) {
;     ...
;             else XB_SPIN(xb_ld(&bar[XB_TOPGEN]) == tg, bar);
;             __builtin_amdgcn_fence(__ATOMIC_ACQUIRE, "agent");
;             xb_add(&bar[XB_XGEN(b.x)], 1u);
;             asm volatile("s_waitcnt vmcnt(0)" ::: "memory");
.LBB0_132:
	s_or_b64 exec, exec, s[10:11]
	v_mov_b32_e32 v1, 0x2000
	v_mov_b32_e32 v2, 1
	s_waitcnt vmcnt(0)
	global_atomic_add v1, v2, s[8:9] offset:1024
	s_waitcnt vmcnt(0)

; __device__ __forceinline__ unsigned xb_ld(unsigned* p)              { return __hip_atomic_load(p, __ATOMIC_RELAXED, __HIP_MEMORY_SCOPE_AGENT); }
; __device__ __forceinline__ unsigned xb_add(unsigned* p, unsigned v) { return __hip_atomic_fetch_add(p, v, __ATOMIC_RELAXED, __HIP_MEMORY_SCOPE_AGENT); }
; #define XB_SPIN(cond, bar) do { unsigned _sp = 0; while (cond) { __builtin_amdgcn_s_sleep(1); \
;     if ((++_sp & 255u) == 0u) { if (xb_ld(&(bar)[XB_TMO])) break; if (_sp > XB_SPIN_CAP) { atomicAdd(&(bar)[XB_TMO], 1u); break; } } } } while (0)
; __device__ __forceinline__ void xcd_barrier(const XcdBarrier& b) {
;     ...
;         if (old + 1u == (gen + 1u) * nloc) {
;             __builtin_amdgcn_fence(__ATOMIC_RELEASE, "agent");
;             asm volatile("s_waitcnt vmcnt(0)" ::: "memory");
;             const unsigned og = xb_add(&bar[XB_TOP], 1u);
;             const unsigned tg = og / nx;
;             if (og + 1u == (tg + 1u) * nx) xb_add(&bar[XB_TOPGEN], 1u);
;             else XB_SPIN(xb_ld(&bar[XB_TOPGEN]) == tg, bar);
.LBB0_512:
	s_or_b64 exec, exec, s[10:11]
	buffer_inv sc1
	v_cvt_f32_u32_e32 v4, v1
	s_waitcnt vmcnt(1)
	v_readfirstlane_b32 s2, v3
	v_readlane_b32 s8, v244, 3
	v_readlane_b32 s10, v244, 5
	v_rcp_iflag_f32_e32 v4, v4
	v_add_u32_e32 v2, s2, v2
	v_add_u32_e32 v5, 1, v2
	v_readlane_b32 s14, v244, 9
	v_mul_f32_e32 v3, 0x4f7ffffe, v4
	v_cvt_u32_f32_e32 v3, v3
	v_sub_u32_e32 v4, 0, v1
	v_readlane_b32 s11, v244, 6
	v_readlane_b32 s15, v244, 10
	v_mul_lo_u32 v4, v4, v3
	v_mul_hi_u32 v4, v3, v4
	v_add_u32_e32 v3, v3, v4
	v_mul_hi_u32 v3, v2, v3
	v_mul_lo_u32 v4, v3, v1
	v_sub_u32_e32 v2, v2, v4
	v_add_u32_e32 v6, 1, v3
	v_cmp_ge_u32_e32 vcc, v2, v1
	v_sub_u32_e32 v4, v2, v1
	s_add_u32 s10, s14, 0x7500
	v_cndmask_b32_e32 v3, v3, v6, vcc
	v_cndmask_b32_e32 v2, v2, v4, vcc
	v_add_u32_e32 v4, 1, v3
	v_cmp_ge_u32_e32 vcc, v2, v1
	v_readlane_b32 s12, v244, 7
	v_readlane_b32 s13, v244, 8
	v_cndmask_b32_e32 v4, v3, v4, vcc
	v_mul_lo_u32 v2, v1, v4
	v_add_u32_e32 v1, v2, v1
	s_addc_u32 s11, s15, 0
	v_cmp_ne_u32_e32 vcc, v5, v1
	v_readlane_b32 s9, v244, 4
	s_mov_b64 s[12:13], -1
	v_mov_b64_e32 v[2:3], s[10:11]
	s_and_saveexec_b64 s[8:9], vcc
	s_cbranch_execz .LBB0_524
	v_mov_b32_e32 v1, 0
	global_load_dword v2, v1, s[10:11] sc1
	s_mov_b64 s[16:17], 0
	s_waitcnt vmcnt(0)
	v_cmp_eq_u32_e32 vcc, v2, v4
	s_and_saveexec_b64 s[14:15], vcc
	s_cbranch_execz .LBB0_523
	v_readlane_b32 s16, v244, 3
	v_readlane_b32 s22, v244, 9
	v_readlane_b32 s17, v244, 4
	v_readlane_b32 s23, v244, 10
	s_add_u32 s12, s22, 0x4200
	v_readlane_b32 s18, v244, 5
	v_readlane_b32 s19, v244, 6
	s_addc_u32 s13, s23, 0
	s_mov_b32 s2, 1
	s_mov_b64 s[16:17], 0
	v_readlane_b32 s20, v244, 7
	v_readlane_b32 s21, v244, 8
	s_branch .LBB0_516

; __device__ __forceinline__ unsigned xb_ld(unsigned* p)              { return __hip_atomic_load(p, __ATOMIC_RELAXED, __HIP_MEMORY_SCOPE_AGENT); }
; __device__ __forceinline__ unsigned xb_add(unsigned* p, unsigned v) { return __hip_atomic_fetch_add(p, v, __ATOMIC_RELAXED, __HIP_MEMORY_SCOPE_AGENT); }
; #define XB_SPIN(cond, bar) do { unsigned _sp = 0; while (cond) { __builtin_amdgcn_s_sleep(1); \
;     if ((++_sp & 255u) == 0u) { if (xb_ld(&(bar)[XB_TMO])) break; if (_sp > XB_SPIN_CAP) { atomicAdd(&(bar)[XB_TMO], 1u); break; } } } } while (0)
; __device__ __forceinline__ void xcd_barrier(const XcdBarrier& b) {
;     ...
;             else XB_SPIN(xb_ld(&bar[XB_TOPGEN]) == tg, bar);
;             __builtin_amdgcn_fence(__ATOMIC_ACQUIRE, "agent");
;             xb_add(&bar[XB_XGEN(b.x)], 1u);
;             asm volatile("s_waitcnt vmcnt(0)" ::: "memory");
.LBB0_526:
	s_or_b64 exec, exec, s[8:9]
	v_mov_b32_e32 v1, 0x2000
	v_mov_b32_e32 v2, 1
	s_waitcnt vmcnt(0)
	global_atomic_add v1, v2, s[6:7] offset:1024
	s_waitcnt vmcnt(0)

; __device__ __forceinline__ unsigned xb_ld(unsigned* p)              { return __hip_atomic_load(p, __ATOMIC_RELAXED, __HIP_MEMORY_SCOPE_AGENT); }
; __device__ __forceinline__ unsigned xb_add(unsigned* p, unsigned v) { return __hip_atomic_fetch_add(p, v, __ATOMIC_RELAXED, __HIP_MEMORY_SCOPE_AGENT); }
; #define XB_SPIN(cond, bar) do { unsigned _sp = 0; while (cond) { __builtin_amdgcn_s_sleep(1); \
;     if ((++_sp & 255u) == 0u) { if (xb_ld(&(bar)[XB_TMO])) break; if (_sp > XB_SPIN_CAP) { atomicAdd(&(bar)[XB_TMO], 1u); break; } } } } while (0)
; __device__ __forceinline__ void xcd_barrier(const XcdBarrier& b) {
;     ...
;         if (old + 1u == (gen + 1u) * nloc) {
;             __builtin_amdgcn_fence(__ATOMIC_RELEASE, "agent");
;             asm volatile("s_waitcnt vmcnt(0)" ::: "memory");
;             const unsigned og = xb_add(&bar[XB_TOP], 1u);
;             const unsigned tg = og / nx;
;             if (og + 1u == (tg + 1u) * nx) xb_add(&bar[XB_TOPGEN], 1u);
;             else XB_SPIN(xb_ld(&bar[XB_TOPGEN]) == tg, bar);
.LBB0_772:
	s_or_b64 exec, exec, s[8:9]
	buffer_inv sc1
	v_cvt_f32_u32_e32 v4, v1
	s_waitcnt vmcnt(1)
	v_readfirstlane_b32 s2, v3
	v_readlane_b32 s8, v244, 3
	v_readlane_b32 s14, v244, 9
	v_rcp_iflag_f32_e32 v4, v4
	v_add_u32_e32 v2, s2, v2
	v_add_u32_e32 v5, 1, v2
	v_readlane_b32 s9, v244, 4
	v_mul_f32_e32 v3, 0x4f7ffffe, v4
	v_cvt_u32_f32_e32 v3, v3
	v_sub_u32_e32 v4, 0, v1
	v_readlane_b32 s15, v244, 10
	s_add_u32 s8, s14, 0x7500
	v_mul_lo_u32 v4, v4, v3
	v_mul_hi_u32 v4, v3, v4
	v_add_u32_e32 v3, v3, v4
	v_mul_hi_u32 v3, v2, v3
	v_mul_lo_u32 v4, v3, v1
	v_sub_u32_e32 v2, v2, v4
	v_add_u32_e32 v6, 1, v3
	v_cmp_ge_u32_e32 vcc, v2, v1
	v_sub_u32_e32 v4, v2, v1
	v_readlane_b32 s10, v244, 5
	v_cndmask_b32_e32 v3, v3, v6, vcc
	v_cndmask_b32_e32 v2, v2, v4, vcc
	v_add_u32_e32 v4, 1, v3
	v_cmp_ge_u32_e32 vcc, v2, v1
	v_readlane_b32 s11, v244, 6
	s_addc_u32 s9, s15, 0
	v_cndmask_b32_e32 v4, v3, v4, vcc
	v_mul_lo_u32 v2, v1, v4
	v_add_u32_e32 v1, v2, v1
	v_cmp_ne_u32_e32 vcc, v5, v1
	s_mov_b64 s[10:11], -1
	v_mov_b64_e32 v[2:3], s[8:9]
	v_readlane_b32 s12, v244, 7
	v_readlane_b32 s13, v244, 8
	s_and_saveexec_b64 s[6:7], vcc
	s_cbranch_execz .LBB0_784
	v_mov_b32_e32 v1, 0
	global_load_dword v2, v1, s[8:9] sc1
	s_mov_b64 s[14:15], 0
	s_waitcnt vmcnt(0)
	v_cmp_eq_u32_e32 vcc, v2, v4
	s_and_saveexec_b64 s[12:13], vcc
	s_cbranch_execz .LBB0_783
	v_readlane_b32 s16, v244, 3
	v_readlane_b32 s22, v244, 9
	v_readlane_b32 s23, v244, 10
	s_add_u32 s10, s22, 0x4200
	v_readlane_b32 s17, v244, 4
	s_addc_u32 s11, s23, 0
	s_mov_b32 s2, 1
	v_readlane_b32 s18, v244, 5
	v_readlane_b32 s19, v244, 6
	v_readlane_b32 s20, v244, 7
	v_readlane_b32 s21, v244, 8
	s_branch .LBB0_776

; __device__ __forceinline__ unsigned xb_ld(unsigned* p)              { return __hip_atomic_load(p, __ATOMIC_RELAXED, __HIP_MEMORY_SCOPE_AGENT); }
; __device__ __forceinline__ unsigned xb_add(unsigned* p, unsigned v) { return __hip_atomic_fetch_add(p, v, __ATOMIC_RELAXED, __HIP_MEMORY_SCOPE_AGENT); }
; #define XB_SPIN(cond, bar) do { unsigned _sp = 0; while (cond) { __builtin_amdgcn_s_sleep(1); \
;     if ((++_sp & 255u) == 0u) { if (xb_ld(&(bar)[XB_TMO])) break; if (_sp > XB_SPIN_CAP) { atomicAdd(&(bar)[XB_TMO], 1u); break; } } } } while (0)
; __device__ __forceinline__ void xcd_barrier(const XcdBarrier& b) {
;     ...
;             else XB_SPIN(xb_ld(&bar[XB_TOPGEN]) == tg, bar);
;             __builtin_amdgcn_fence(__ATOMIC_ACQUIRE, "agent");
;             xb_add(&bar[XB_XGEN(b.x)], 1u);
;             asm volatile("s_waitcnt vmcnt(0)" ::: "memory");
.LBB0_786:
	s_or_b64 exec, exec, s[6:7]
	v_mov_b32_e32 v1, 0x2000
	v_mov_b32_e32 v2, 1
	s_waitcnt vmcnt(0)
	global_atomic_add v1, v2, s[4:5] offset:1024
	s_waitcnt vmcnt(0)

; __device__ __forceinline__ unsigned xb_ld(unsigned* p)              { return __hip_atomic_load(p, __ATOMIC_RELAXED, __HIP_MEMORY_SCOPE_AGENT); }
; __device__ __forceinline__ unsigned xb_add(unsigned* p, unsigned v) { return __hip_atomic_fetch_add(p, v, __ATOMIC_RELAXED, __HIP_MEMORY_SCOPE_AGENT); }
; #define XB_SPIN(cond, bar) do { unsigned _sp = 0; while (cond) { __builtin_amdgcn_s_sleep(1); \
;     if ((++_sp & 255u) == 0u) { if (xb_ld(&(bar)[XB_TMO])) break; if (_sp > XB_SPIN_CAP) { atomicAdd(&(bar)[XB_TMO], 1u); break; } } } } while (0)
; __device__ __forceinline__ void xcd_barrier(const XcdBarrier& b) {
;     ...
;         if (old + 1u == (gen + 1u) * nloc) {
;             __builtin_amdgcn_fence(__ATOMIC_RELEASE, "agent");
;             asm volatile("s_waitcnt vmcnt(0)" ::: "memory");
;             const unsigned og = xb_add(&bar[XB_TOP], 1u);
;             const unsigned tg = og / nx;
;             if (og + 1u == (tg + 1u) * nx) xb_add(&bar[XB_TOPGEN], 1u);
;             else XB_SPIN(xb_ld(&bar[XB_TOPGEN]) == tg, bar);
.LBB0_1858:
	s_or_b64 exec, exec, s[10:11]
	buffer_inv sc1
	v_cvt_f32_u32_e32 v4, v1
	s_waitcnt vmcnt(1)
	v_readfirstlane_b32 s2, v3
	v_readlane_b32 s8, v244, 3
	v_readlane_b32 s10, v244, 5
	v_rcp_iflag_f32_e32 v4, v4
	v_add_u32_e32 v2, s2, v2
	v_add_u32_e32 v5, 1, v2
	v_readlane_b32 s14, v244, 9
	v_mul_f32_e32 v3, 0x4f7ffffe, v4
	v_cvt_u32_f32_e32 v3, v3
	v_sub_u32_e32 v4, 0, v1
	v_readlane_b32 s11, v244, 6
	v_readlane_b32 s15, v244, 10
	v_mul_lo_u32 v4, v4, v3
	v_mul_hi_u32 v4, v3, v4
	v_add_u32_e32 v3, v3, v4
	v_mul_hi_u32 v3, v2, v3
	v_mul_lo_u32 v4, v3, v1
	v_sub_u32_e32 v2, v2, v4
	v_add_u32_e32 v6, 1, v3
	v_cmp_ge_u32_e32 vcc, v2, v1
	v_sub_u32_e32 v4, v2, v1
	s_add_u32 s10, s14, 0x7500
	v_cndmask_b32_e32 v3, v3, v6, vcc
	v_cndmask_b32_e32 v2, v2, v4, vcc
	v_add_u32_e32 v4, 1, v3
	v_cmp_ge_u32_e32 vcc, v2, v1
	v_readlane_b32 s12, v244, 7
	v_readlane_b32 s13, v244, 8
	v_cndmask_b32_e32 v4, v3, v4, vcc
	v_mul_lo_u32 v2, v1, v4
	v_add_u32_e32 v1, v2, v1
	s_addc_u32 s11, s15, 0
	v_cmp_ne_u32_e32 vcc, v5, v1
	v_readlane_b32 s9, v244, 4
	s_mov_b64 s[12:13], -1
	v_mov_b64_e32 v[2:3], s[10:11]
	s_and_saveexec_b64 s[8:9], vcc
	s_cbranch_execz .LBB0_1870
	v_mov_b32_e32 v1, 0
	global_load_dword v2, v1, s[10:11] sc1
	s_mov_b64 s[16:17], 0
	s_waitcnt vmcnt(0)
	v_cmp_eq_u32_e32 vcc, v2, v4
	s_and_saveexec_b64 s[14:15], vcc
	s_cbranch_execz .LBB0_1869
	v_readlane_b32 s16, v244, 3
	v_readlane_b32 s17, v244, 4
	v_readlane_b32 s18, v244, 5
	v_readlane_b32 s19, v244, 6
	v_readlane_b32 s20, v244, 7
	v_readlane_b32 s21, v244, 8
	v_readlane_b32 s22, v244, 9
	v_readlane_b32 s23, v244, 10
	s_mov_b64 s[16:17], s[20:21]
	s_mov_b64 s[18:19], s[22:23]
	s_add_u32 s12, s18, 0x4200
	s_addc_u32 s13, s19, 0
	s_mov_b32 s2, 1
	s_mov_b64 s[16:17], 0
	s_branch .LBB0_1862

; __device__ __forceinline__ unsigned xb_ld(unsigned* p)              { return __hip_atomic_load(p, __ATOMIC_RELAXED, __HIP_MEMORY_SCOPE_AGENT); }
; __device__ __forceinline__ unsigned xb_add(unsigned* p, unsigned v) { return __hip_atomic_fetch_add(p, v, __ATOMIC_RELAXED, __HIP_MEMORY_SCOPE_AGENT); }
; #define XB_SPIN(cond, bar) do { unsigned _sp = 0; while (cond) { __builtin_amdgcn_s_sleep(1); \
;     if ((++_sp & 255u) == 0u) { if (xb_ld(&(bar)[XB_TMO])) break; if (_sp > XB_SPIN_CAP) { atomicAdd(&(bar)[XB_TMO], 1u); break; } } } } while (0)
; __device__ __forceinline__ void xcd_barrier(const XcdBarrier& b) {
;     ...
;         if (old + 1u == (gen + 1u) * nloc) {
;             __builtin_amdgcn_fence(__ATOMIC_RELEASE, "agent");
;             asm volatile("s_waitcnt vmcnt(0)" ::: "memory");
;             const unsigned og = xb_add(&bar[XB_TOP], 1u);
;             const unsigned tg = og / nx;
;             if (og + 1u == (tg + 1u) * nx) xb_add(&bar[XB_TOPGEN], 1u);
;             else XB_SPIN(xb_ld(&bar[XB_TOPGEN]) == tg, bar);
.LBB0_1912:
	s_or_b64 exec, exec, s[10:11]
	buffer_inv sc1
	v_cvt_f32_u32_e32 v4, v1
	s_waitcnt vmcnt(1)
	v_readfirstlane_b32 s2, v3
	v_readlane_b32 s8, v244, 3
	v_readlane_b32 s9, v244, 4
	v_rcp_iflag_f32_e32 v4, v4
	v_add_u32_e32 v2, s2, v2
	v_add_u32_e32 v5, 1, v2
	v_readlane_b32 s10, v244, 5
	v_mul_f32_e32 v3, 0x4f7ffffe, v4
	v_cvt_u32_f32_e32 v3, v3
	v_sub_u32_e32 v4, 0, v1
	v_readlane_b32 s11, v244, 6
	v_readlane_b32 s12, v244, 7
	v_mul_lo_u32 v4, v4, v3
	v_mul_hi_u32 v4, v3, v4
	v_add_u32_e32 v3, v3, v4
	v_mul_hi_u32 v3, v2, v3
	v_mul_lo_u32 v4, v3, v1
	v_sub_u32_e32 v2, v2, v4
	v_add_u32_e32 v6, 1, v3
	v_cmp_ge_u32_e32 vcc, v2, v1
	v_sub_u32_e32 v4, v2, v1
	v_readlane_b32 s13, v244, 8
	v_cndmask_b32_e32 v3, v3, v6, vcc
	v_cndmask_b32_e32 v2, v2, v4, vcc
	v_add_u32_e32 v4, 1, v3
	v_cmp_ge_u32_e32 vcc, v2, v1
	v_readlane_b32 s14, v244, 9
	v_readlane_b32 s15, v244, 10
	s_mov_b64 s[8:9], s[12:13]
	v_cndmask_b32_e32 v4, v3, v4, vcc
	s_mov_b64 s[10:11], s[14:15]
	v_mul_lo_u32 v2, v1, v4
	s_add_u32 s10, s10, 0x7500
	v_add_u32_e32 v1, v2, v1
	s_addc_u32 s11, s11, 0
	v_cmp_ne_u32_e32 vcc, v5, v1
	s_mov_b64 s[12:13], -1
	v_mov_b64_e32 v[2:3], s[10:11]
	s_and_saveexec_b64 s[8:9], vcc
	s_cbranch_execz .LBB0_1924
	v_mov_b32_e32 v1, 0
	global_load_dword v2, v1, s[10:11] sc1
	s_mov_b64 s[16:17], 0
	s_waitcnt vmcnt(0)
	v_cmp_eq_u32_e32 vcc, v2, v4
	s_and_saveexec_b64 s[14:15], vcc
	s_cbranch_execz .LBB0_1923
	v_readlane_b32 s16, v244, 3
	v_readlane_b32 s17, v244, 4
	v_readlane_b32 s18, v244, 5
	v_readlane_b32 s19, v244, 6
	v_readlane_b32 s20, v244, 7
	v_readlane_b32 s21, v244, 8
	v_readlane_b32 s22, v244, 9
	v_readlane_b32 s23, v244, 10
	s_mov_b64 s[16:17], s[20:21]
	s_mov_b64 s[18:19], s[22:23]
	s_add_u32 s12, s18, 0x4200
	s_addc_u32 s13, s19, 0
	s_mov_b32 s2, 1
	s_mov_b64 s[16:17], 0
	s_branch .LBB0_1916

; __device__ __forceinline__ unsigned xb_ld(unsigned* p)              { return __hip_atomic_load(p, __ATOMIC_RELAXED, __HIP_MEMORY_SCOPE_AGENT); }
; __device__ __forceinline__ unsigned xb_add(unsigned* p, unsigned v) { return __hip_atomic_fetch_add(p, v, __ATOMIC_RELAXED, __HIP_MEMORY_SCOPE_AGENT); }
; #define XB_SPIN(cond, bar) do { unsigned _sp = 0; while (cond) { __builtin_amdgcn_s_sleep(1); \
;     if ((++_sp & 255u) == 0u) { if (xb_ld(&(bar)[XB_TMO])) break; if (_sp > XB_SPIN_CAP) { atomicAdd(&(bar)[XB_TMO], 1u); break; } } } } while (0)
; __device__ __forceinline__ void xcd_barrier(const XcdBarrier& b) {
;     ...
;         if (old + 1u == (gen + 1u) * nloc) {
;             __builtin_amdgcn_fence(__ATOMIC_RELEASE, "agent");
;             asm volatile("s_waitcnt vmcnt(0)" ::: "memory");
;             const unsigned og = xb_add(&bar[XB_TOP], 1u);
;             const unsigned tg = og / nx;
;             if (og + 1u == (tg + 1u) * nx) xb_add(&bar[XB_TOPGEN], 1u);
;             else XB_SPIN(xb_ld(&bar[XB_TOPGEN]) == tg, bar);
.LBB0_2233:
	s_or_b64 exec, exec, s[6:7]
	buffer_inv sc1
	v_cvt_f32_u32_e32 v3, v0
	s_waitcnt vmcnt(1)
	v_readfirstlane_b32 s4, v2
	v_rcp_iflag_f32_e32 v3, v3
	s_nop 0
	v_add_u32_e32 v1, s4, v1
	v_add_u32_e32 v4, 1, v1
	v_readlane_b32 s4, v244, 3
	v_mul_f32_e32 v2, 0x4f7ffffe, v3
	v_cvt_u32_f32_e32 v2, v2
	v_sub_u32_e32 v3, 0, v0
	v_readlane_b32 s6, v244, 5
	v_readlane_b32 s7, v244, 6
	v_mul_lo_u32 v3, v3, v2
	v_mul_hi_u32 v3, v2, v3
	v_add_u32_e32 v2, v2, v3
	v_mul_hi_u32 v2, v1, v2
	v_mul_lo_u32 v3, v2, v0
	v_sub_u32_e32 v1, v1, v3
	v_add_u32_e32 v5, 1, v2
	v_cmp_ge_u32_e32 vcc, v1, v0
	v_sub_u32_e32 v3, v1, v0
	v_readlane_b32 s10, v244, 9
	v_cndmask_b32_e32 v2, v2, v5, vcc
	v_cndmask_b32_e32 v1, v1, v3, vcc
	v_add_u32_e32 v3, 1, v2
	v_cmp_ge_u32_e32 vcc, v1, v0
	v_readlane_b32 s11, v244, 10
	s_mov_b64 s[6:7], s[10:11]
	v_cndmask_b32_e32 v2, v2, v3, vcc
	v_mul_lo_u32 v1, v0, v2
	s_add_u32 s6, s6, 0x7500
	v_add_u32_e32 v0, v1, v0
	v_readlane_b32 s8, v244, 7
	v_readlane_b32 s9, v244, 8
	s_addc_u32 s7, s7, 0
	v_cmp_ne_u32_e32 vcc, v4, v0
	v_readlane_b32 s5, v244, 4
	s_mov_b64 s[8:9], -1
	v_mov_b64_e32 v[0:1], s[6:7]
	s_and_saveexec_b64 s[4:5], vcc
	s_cbranch_execz .LBB0_2245
	v_mov_b32_e32 v0, 0
	global_load_dword v1, v0, s[6:7] sc1
	s_mov_b64 s[12:13], 0
	s_waitcnt vmcnt(0)
	v_cmp_eq_u32_e32 vcc, v1, v2
	s_and_saveexec_b64 s[10:11], vcc
	s_cbranch_execz .LBB0_2244
	v_readlane_b32 s12, v244, 3
	v_readlane_b32 s14, v244, 5
	v_readlane_b32 s15, v244, 6
	v_readlane_b32 s18, v244, 9
	v_readlane_b32 s19, v244, 10
	s_mov_b64 s[14:15], s[18:19]
	v_readlane_b32 s13, v244, 4
	s_add_u32 s8, s14, 0x4200
	s_addc_u32 s9, s15, 0
	s_mov_b32 s22, 1
	s_mov_b64 s[12:13], 0
	v_readlane_b32 s16, v244, 7
	v_readlane_b32 s17, v244, 8
	s_branch .LBB0_2237

; __device__ __forceinline__ unsigned xb_ld(unsigned* p)              { return __hip_atomic_load(p, __ATOMIC_RELAXED, __HIP_MEMORY_SCOPE_AGENT); }
; __device__ __forceinline__ unsigned xb_add(unsigned* p, unsigned v) { return __hip_atomic_fetch_add(p, v, __ATOMIC_RELAXED, __HIP_MEMORY_SCOPE_AGENT); }
; #define XB_SPIN(cond, bar) do { unsigned _sp = 0; while (cond) { __builtin_amdgcn_s_sleep(1); \
;     if ((++_sp & 255u) == 0u) { if (xb_ld(&(bar)[XB_TMO])) break; if (_sp > XB_SPIN_CAP) { atomicAdd(&(bar)[XB_TMO], 1u); break; } } } } while (0)
; __device__ __forceinline__ void xcd_barrier(const XcdBarrier& b) {
;     ...
;             else XB_SPIN(xb_ld(&bar[XB_TOPGEN]) == tg, bar);
;             __builtin_amdgcn_fence(__ATOMIC_ACQUIRE, "agent");
;             xb_add(&bar[XB_XGEN(b.x)], 1u);
;             asm volatile("s_waitcnt vmcnt(0)" ::: "memory");
.LBB0_2247:
	s_or_b64 exec, exec, s[4:5]
	v_mov_b32_e32 v0, 0x2000
	v_mov_b32_e32 v1, 1
	s_waitcnt vmcnt(0)
	global_atomic_add v0, v1, s[2:3] offset:1024
	s_waitcnt vmcnt(0)
